# NSA selected/window sweeps: V-transpose fragments prefetched 4 deep in the PV section; lane^32 max/sum exchanges use v_permlane32_swap instead of ds_bpermute
# baseline (speedup 1.0000x reference)
.LBB0_317:
	v_lshl_add_u32 v2, s0, 6, v203
	s_movk_i32 s13, 0x1400
	v_mad_i64_i32 v[0:1], s[0:1], v2, s13, 0
	v_or_b32_e32 v0, v0, v148
	v_lshl_add_u64 v[0:1], v[0:1], 1, v[146:147]
	global_load_dwordx4 v[128:131], v[0:1], off offset:3072
	global_load_dwordx4 v[132:135], v[0:1], off offset:3584
	v_add_u32_e32 v0, 32, v2
	v_mad_i64_i32 v[0:1], s[0:1], v0, s13, 0
	v_or_b32_e32 v0, v0, v148
	v_lshl_add_u64 v[0:1], v[0:1], 1, v[146:147]
	global_load_dwordx4 v[136:139], v[0:1], off offset:3072
	global_load_dwordx4 v[140:143], v[0:1], off offset:3584
	v_add3_u32 v8, v178, v201, v202
	ds_read_b128 v[0:3], v8
	ds_read_b128 v[4:7], v8 offset:32
	ds_read_b128 v[12:15], v8 offset:64
	ds_read_b128 v[16:19], v8 offset:96
	ds_read_b128 v[20:23], v8 offset:4608
	ds_read_b128 v[24:27], v8 offset:4640
	ds_read_b128 v[28:31], v8 offset:4672
	ds_read_b128 v[8:11], v8 offset:4704
	s_mov_b64 s[14:15], -1
	s_cmp_lg_u32 s51, s20
	s_waitcnt lgkmcnt(7)
	v_mfma_f32_32x32x16_bf16 v[112:127], v[0:3], v[160:163], 0
	s_waitcnt lgkmcnt(6)
	v_mfma_f32_32x32x16_bf16 v[112:127], v[4:7], v[164:167], v[112:127]
	s_waitcnt lgkmcnt(5)
	v_mfma_f32_32x32x16_bf16 v[112:127], v[12:15], v[168:171], v[112:127]
	s_waitcnt lgkmcnt(4)
	v_mfma_f32_32x32x16_bf16 v[112:127], v[16:19], v[172:175], v[112:127]
	s_waitcnt lgkmcnt(3)
	v_mfma_f32_32x32x16_bf16 v[96:111], v[20:23], v[160:163], 0
	s_waitcnt lgkmcnt(2)
	v_mfma_f32_32x32x16_bf16 v[96:111], v[24:27], v[164:167], v[96:111]
	s_waitcnt lgkmcnt(1)
	v_mfma_f32_32x32x16_bf16 v[96:111], v[28:31], v[168:171], v[96:111]
	s_waitcnt lgkmcnt(0)
	v_mfma_f32_32x32x16_bf16 v[96:111], v[8:11], v[172:175], v[96:111]
	s_cbranch_scc0 .LBB0_319
	s_nop 10
	v_max_f32_e32 v0, v96, v96
	v_max_f32_e32 v1, v112, v112
	v_max_f32_e32 v0, v1, v0
	v_max3_f32 v0, v0, v113, v97
	v_max3_f32 v0, v0, v114, v98
	v_max3_f32 v0, v0, v115, v99
	v_max3_f32 v0, v0, v116, v100
	v_max3_f32 v0, v0, v117, v101
	v_max3_f32 v0, v0, v118, v102
	v_max3_f32 v0, v0, v119, v103
	v_max3_f32 v0, v0, v120, v104
	v_max3_f32 v0, v0, v121, v105
	v_max3_f32 v0, v0, v122, v106
	v_max3_f32 v0, v0, v123, v107
	v_max3_f32 v0, v0, v124, v108
	v_max3_f32 v0, v0, v125, v109
	v_max3_f32 v0, v0, v126, v110
	v_max3_f32 v0, v0, v127, v111
	v_mov_b32_e32 v1, v0
	v_bfe_u32 v2, v154, s51, 1
	v_cmp_eq_u32_e32 vcc, 0, v2
	v_max_f32_e32 v3, v180, v180
	s_mov_b64 s[14:15], 0
	v_permlane32_swap_b32_e32 v0, v1
	v_max_f32_e32 v1, v1, v1
	v_max_f32_e32 v0, v0, v1
	v_mul_f32_e32 v0, 0x3e38aa3b, v0
	v_cndmask_b32_e32 v0, v0, v215, vcc
	v_max_f32_e32 v181, v3, v0
	v_sub_f32_e32 v0, v180, v181
	v_cndmask_b32_e64 v30, v232, 0, vcc
	v_cndmask_b32_e64 v182, -v181, v215, vcc
	v_exp_f32_e32 v150, v0
	v_pk_fma_f32 v[0:1], v[30:31], v[112:113], v[182:183] op_sel_hi:[0,1,0]
	v_exp_f32_e32 v0, v0
	v_exp_f32_e32 v1, v1
	v_pk_fma_f32 v[2:3], v[30:31], v[114:115], v[182:183] op_sel_hi:[0,1,0]
	v_exp_f32_e32 v2, v2
	v_exp_f32_e32 v3, v3
	v_pk_fma_f32 v[4:5], v[30:31], v[116:117], v[182:183] op_sel_hi:[0,1,0]
	v_exp_f32_e32 v4, v4
	v_exp_f32_e32 v5, v5
	v_pk_fma_f32 v[6:7], v[30:31], v[118:119], v[182:183] op_sel_hi:[0,1,0]
	v_exp_f32_e32 v6, v6
	v_exp_f32_e32 v7, v7
	v_pk_add_f32 v[8:9], v[0:1], 0 op_sel_hi:[1,0]
	v_pk_fma_f32 v[10:11], v[30:31], v[122:123], v[182:183] op_sel_hi:[0,1,0]
	v_pk_add_f32 v[8:9], v[2:3], v[8:9]
	v_exp_f32_e32 v10, v10
	v_pk_add_f32 v[8:9], v[4:5], v[8:9]
	v_exp_f32_e32 v11, v11
	v_pk_add_f32 v[16:17], v[6:7], v[8:9]
	v_pk_fma_f32 v[8:9], v[30:31], v[120:121], v[182:183] op_sel_hi:[0,1,0]
	v_exp_f32_e32 v8, v8
	v_exp_f32_e32 v9, v9
	v_pk_fma_f32 v[12:13], v[30:31], v[124:125], v[182:183] op_sel_hi:[0,1,0]
	v_exp_f32_e32 v12, v12
	v_exp_f32_e32 v13, v13
	v_pk_fma_f32 v[14:15], v[30:31], v[126:127], v[182:183] op_sel_hi:[0,1,0]
	v_exp_f32_e32 v14, v14
	v_exp_f32_e32 v15, v15
	v_pk_add_f32 v[16:17], v[8:9], v[16:17]
	v_pk_fma_f32 v[18:19], v[30:31], v[98:99], v[182:183] op_sel_hi:[0,1,0]
	v_pk_add_f32 v[16:17], v[10:11], v[16:17]
	v_exp_f32_e32 v18, v18
	v_pk_add_f32 v[16:17], v[12:13], v[16:17]
	v_exp_f32_e32 v19, v19
	v_pk_add_f32 v[24:25], v[14:15], v[16:17]
	v_pk_fma_f32 v[16:17], v[30:31], v[96:97], v[182:183] op_sel_hi:[0,1,0]
	v_exp_f32_e32 v16, v16
	v_exp_f32_e32 v17, v17
	v_pk_fma_f32 v[20:21], v[30:31], v[100:101], v[182:183] op_sel_hi:[0,1,0]
	v_exp_f32_e32 v20, v20
	v_exp_f32_e32 v21, v21
	v_pk_fma_f32 v[22:23], v[30:31], v[102:103], v[182:183] op_sel_hi:[0,1,0]
	v_exp_f32_e32 v22, v22
	v_exp_f32_e32 v23, v23
	v_pk_add_f32 v[24:25], v[16:17], v[24:25]
	v_pk_fma_f32 v[26:27], v[30:31], v[106:107], v[182:183] op_sel_hi:[0,1,0]
	v_pk_add_f32 v[24:25], v[18:19], v[24:25]
	v_exp_f32_e32 v26, v26
	v_pk_add_f32 v[24:25], v[20:21], v[24:25]
	v_exp_f32_e32 v27, v27
	v_pk_add_f32 v[184:185], v[22:23], v[24:25]
	v_pk_fma_f32 v[24:25], v[30:31], v[104:105], v[182:183] op_sel_hi:[0,1,0]
	v_exp_f32_e32 v24, v24
	v_exp_f32_e32 v25, v25
	v_pk_fma_f32 v[28:29], v[30:31], v[108:109], v[182:183] op_sel_hi:[0,1,0]
	v_exp_f32_e32 v28, v28
	v_exp_f32_e32 v29, v29
	v_pk_fma_f32 v[30:31], v[30:31], v[110:111], v[182:183] op_sel_hi:[0,1,0]
	v_exp_f32_e32 v30, v30
	v_exp_f32_e32 v31, v31
	v_pk_add_f32 v[182:183], v[24:25], v[184:185]
	s_nop 0
	v_pk_add_f32 v[182:183], v[26:27], v[182:183]
	s_nop 0
	v_pk_add_f32 v[182:183], v[28:29], v[182:183]
	s_nop 0
	v_pk_add_f32 v[182:183], v[30:31], v[182:183]
	s_nop 0
	v_add_f32_e32 v182, v182, v183

.LBB0_321:
	s_nop 8
	v_mov_b32_e32 v96, v182
	v_cvt_pk_bf16_f32 v98, v4, v5
	v_cvt_pk_bf16_f32 v4, v16, v17
	v_add3_u32 v16, v178, v157, v158
	v_cvt_pk_bf16_f32 v8, v8, v9
	v_cvt_pk_bf16_f32 v9, v10, v11
	v_cvt_pk_bf16_f32 v10, v12, v13
	v_cvt_pk_bf16_f32 v11, v14, v15
	ds_read_b64_tr_b16 v[12:13], v16 offset:9216
	ds_read_b64_tr_b16 v[14:15], v16 offset:10368
	v_permlane32_swap_b32_e32 v182, v96
	v_add_f32_e32 v209, v182, v96
	v_cvt_pk_bf16_f32 v96, v0, v1
	v_cvt_pk_bf16_f32 v97, v2, v3
	v_cvt_pk_bf16_f32 v99, v6, v7
	v_cvt_pk_bf16_f32 v5, v18, v19
	v_cvt_pk_bf16_f32 v6, v20, v21
	v_cvt_pk_bf16_f32 v7, v22, v23
	v_cvt_pk_bf16_f32 v0, v24, v25
	v_cvt_pk_bf16_f32 v1, v26, v27
	v_cvt_pk_bf16_f32 v2, v28, v29
	v_cvt_pk_bf16_f32 v3, v30, v31
	ds_read_b64_tr_b16 v[18:19], v16 offset:11520
	ds_read_b64_tr_b16 v[20:21], v16 offset:12672
	ds_read_b64_tr_b16 v[22:23], v16 offset:13824
	ds_read_b64_tr_b16 v[24:25], v16 offset:14976
	ds_read_b64_tr_b16 v[26:27], v16 offset:16128
	ds_read_b64_tr_b16 v[28:29], v16 offset:17280
	v_pk_mul_f32 v[64:65], v[64:65], v[150:151] op_sel_hi:[1,0]
	v_pk_mul_f32 v[66:67], v[150:151], v[66:67] op_sel_hi:[0,1]
	v_pk_mul_f32 v[68:69], v[150:151], v[68:69] op_sel_hi:[0,1]
	v_pk_mul_f32 v[70:71], v[150:151], v[70:71] op_sel_hi:[0,1]
	v_pk_mul_f32 v[72:73], v[150:151], v[72:73] op_sel_hi:[0,1]
	v_pk_mul_f32 v[74:75], v[150:151], v[74:75] op_sel_hi:[0,1]
	v_pk_mul_f32 v[76:77], v[150:151], v[76:77] op_sel_hi:[0,1]
	v_pk_mul_f32 v[78:79], v[150:151], v[78:79] op_sel_hi:[0,1]
	s_nop 1
	s_waitcnt lgkmcnt(6)
	v_mfma_f32_32x32x16_bf16 v[64:79], v[12:15], v[96:99], v[64:79]
	ds_read_b64_tr_b16 v[12:13], v16 offset:9280
	ds_read_b64_tr_b16 v[14:15], v16 offset:10432
	v_pk_mul_f32 v[80:81], v[80:81], v[150:151] op_sel_hi:[1,0]
	s_nop 1
	s_waitcnt lgkmcnt(6)
	v_mfma_f32_32x32x16_bf16 v[64:79], v[18:21], v[8:11], v[64:79]
	ds_read_b64_tr_b16 v[18:19], v16 offset:11584
	ds_read_b64_tr_b16 v[20:21], v16 offset:12736
	v_mul_f32_e64 v82, v150, v82
	v_mul_f32_e64 v83, v150, v83
	v_mul_f32_e64 v84, v150, v84
	v_mul_f32_e64 v85, v150, v85
	v_pk_mul_f32 v[86:87], v[150:151], v[86:87] op_sel_hi:[0,1]
	v_pk_mul_f32 v[88:89], v[150:151], v[88:89] op_sel_hi:[0,1]
	v_pk_mul_f32 v[90:91], v[150:151], v[90:91] op_sel_hi:[0,1]
	v_pk_mul_f32 v[92:93], v[150:151], v[92:93] op_sel_hi:[0,1]
	s_nop 1
	s_waitcnt lgkmcnt(6)
	v_mfma_f32_32x32x16_bf16 v[64:79], v[22:25], v[4:7], v[64:79]
	ds_read_b64_tr_b16 v[22:23], v16 offset:13888
	ds_read_b64_tr_b16 v[24:25], v16 offset:15040
	v_mul_f32_e64 v94, v150, v94
	v_mul_f32_e64 v95, v150, v95
	v_fmac_f32_e32 v209, v179, v150
	s_andn2_b64 vcc, exec, s[36:37]
	s_nop 1
	s_waitcnt lgkmcnt(6)
	v_mfma_f32_32x32x16_bf16 v[64:79], v[26:29], v[0:3], v[64:79]
	ds_read_b64_tr_b16 v[26:27], v16 offset:16192
	ds_read_b64_tr_b16 v[28:29], v16 offset:17344
	s_waitcnt lgkmcnt(6)
	v_mfma_f32_32x32x16_bf16 v[80:95], v[12:15], v[96:99], v[80:95]
	s_waitcnt lgkmcnt(4)
	v_mfma_f32_32x32x16_bf16 v[80:95], v[18:21], v[8:11], v[80:95]
	s_waitcnt lgkmcnt(2)
	v_mfma_f32_32x32x16_bf16 v[80:95], v[22:25], v[4:7], v[80:95]
	s_waitcnt lgkmcnt(0)
	v_mfma_f32_32x32x16_bf16 v[80:95], v[26:29], v[0:3], v[80:95]
	v_cndmask_b32_e64 v0, 0, 1, s[38:39]
	v_xor_b32_e32 v177, v177, v0
	s_cbranch_vccz .LBB0_323
	v_mov_b32_e32 v179, v209
	v_mov_b32_e32 v180, v181
	s_mov_b32 s51, s50
	s_branch .LBB0_299

.LBB0_326:
	s_mov_b32 s4, s0
	s_add_i32 s0, s0, 1
	s_cmp_gt_i32 s0, s1
	s_cselect_b64 s[6:7], -1, 0
	s_cmp_le_i32 s0, s1
	s_movk_i32 s5, 0x4800
	s_cselect_b64 s[8:9], -1, 0
	v_mul_lo_u32 v0, v241, s5
	s_and_b64 s[12:13], s[8:9], exec
	v_add_u32_e32 v242, 0, v0
	s_cselect_b32 s5, s0, s4
	v_add3_u32 v0, v242, v235, v239
	v_lshl_add_u32 v2, s5, 6, v203
	s_movk_i32 s5, 0x1400
	s_waitcnt vmcnt(3)
	ds_write_b128 v0, v[176:179]
	s_waitcnt vmcnt(2)
	ds_write_b128 v0, v[180:183] offset:9216
	s_waitcnt vmcnt(1)
	ds_write_b128 v0, v[184:187] offset:4608
	s_waitcnt vmcnt(0)
	ds_write_b128 v0, v[188:191] offset:13824
	v_mad_i64_i32 v[0:1], s[12:13], v2, s5, 0
	v_or_b32_e32 v0, v0, v214
	v_lshl_add_u64 v[0:1], v[0:1], 1, v[212:213]
	s_waitcnt lgkmcnt(0)
	s_barrier
	global_load_dwordx4 v[176:179], v[0:1], off
	global_load_dwordx4 v[180:183], v[0:1], off offset:512
	v_add_u32_e32 v0, 32, v2
	v_mad_i64_i32 v[0:1], s[12:13], v0, s5, 0
	v_or_b32_e32 v0, v0, v214
	v_lshl_add_u64 v[0:1], v[0:1], 1, v[212:213]
	global_load_dwordx4 v[184:187], v[0:1], off
	global_load_dwordx4 v[188:191], v[0:1], off offset:512
	v_add3_u32 v8, v242, v201, v202
	ds_read_b128 v[0:3], v8
	ds_read_b128 v[4:7], v8 offset:32
	ds_read_b128 v[12:15], v8 offset:64
	ds_read_b128 v[16:19], v8 offset:96
	ds_read_b128 v[20:23], v8 offset:4608
	ds_read_b128 v[24:27], v8 offset:4640
	ds_read_b128 v[28:31], v8 offset:4672
	ds_read_b128 v[8:11], v8 offset:4704
	s_cmp_eq_u32 s20, s4
	s_cselect_b64 s[4:5], -1, 0
	s_cmp_lt_i32 s10, s2
	s_cselect_b64 s[12:13], -1, 0
	s_or_b64 s[12:13], s[4:5], s[12:13]
	s_mov_b64 s[4:5], -1
	s_andn2_b64 vcc, exec, s[12:13]
	s_waitcnt lgkmcnt(7)
	v_mfma_f32_32x32x16_bf16 v[144:159], v[0:3], v[160:163], 0
	s_waitcnt lgkmcnt(6)
	v_mfma_f32_32x32x16_bf16 v[144:159], v[4:7], v[164:167], v[144:159]
	s_waitcnt lgkmcnt(5)
	v_mfma_f32_32x32x16_bf16 v[144:159], v[12:15], v[168:171], v[144:159]
	s_waitcnt lgkmcnt(4)
	v_mfma_f32_32x32x16_bf16 v[144:159], v[16:19], v[172:175], v[144:159]
	s_waitcnt lgkmcnt(3)
	v_mfma_f32_32x32x16_bf16 v[128:143], v[20:23], v[160:163], 0
	s_waitcnt lgkmcnt(2)
	v_mfma_f32_32x32x16_bf16 v[128:143], v[24:27], v[164:167], v[128:143]
	s_waitcnt lgkmcnt(1)
	v_mfma_f32_32x32x16_bf16 v[128:143], v[28:31], v[168:171], v[128:143]
	s_waitcnt lgkmcnt(0)
	v_mfma_f32_32x32x16_bf16 v[128:143], v[8:11], v[172:175], v[128:143]
	s_cbranch_vccz .LBB0_328
	s_nop 10
	v_max_f32_e32 v0, v128, v128
	v_max_f32_e32 v1, v144, v144
	v_max_f32_e32 v0, v1, v0
	v_max3_f32 v0, v0, v145, v129
	v_max3_f32 v0, v0, v146, v130
	v_max3_f32 v0, v0, v147, v131
	v_max3_f32 v0, v0, v148, v132
	v_max3_f32 v0, v0, v149, v133
	v_max3_f32 v0, v0, v150, v134
	v_max3_f32 v0, v0, v151, v135
	v_max3_f32 v0, v0, v152, v136
	v_max3_f32 v0, v0, v153, v137
	v_max3_f32 v0, v0, v154, v138
	v_max3_f32 v0, v0, v155, v139
	v_max3_f32 v0, v0, v156, v140
	v_max3_f32 v0, v0, v157, v141
	v_max3_f32 v0, v0, v158, v142
	v_max3_f32 v0, v0, v159, v143
	v_mov_b32_e32 v1, v0
	s_mov_b32 s4, 0x3e38aa3b
	s_nop 1
	v_permlane32_swap_b32_e32 v0, v1
	v_max_f32_e32 v1, v1, v1
	v_max_f32_e32 v0, v0, v1
	v_mul_f32_e32 v0, 0x3e38aa3b, v0
	v_max_f32_e32 v1, v244, v244
	v_max_f32_e32 v216, v1, v0
	v_pk_fma_f32 v[0:1], v[144:145], s[4:5], v[216:217] op_sel_hi:[1,0,0] neg_lo:[0,0,1] neg_hi:[0,0,1]
	v_pk_fma_f32 v[2:3], v[146:147], s[4:5], v[216:217] op_sel_hi:[1,0,0] neg_lo:[0,0,1] neg_hi:[0,0,1]
	v_exp_f32_e32 v0, v0
	v_exp_f32_e32 v1, v1
	v_exp_f32_e32 v2, v2
	v_exp_f32_e32 v3, v3
	v_sub_f32_e32 v218, v244, v216
	v_pk_add_f32 v[4:5], v[0:1], 0 op_sel_hi:[1,0]
	v_exp_f32_e32 v218, v218
	v_pk_add_f32 v[6:7], v[2:3], v[4:5]
	v_pk_fma_f32 v[4:5], v[148:149], s[4:5], v[216:217] op_sel_hi:[1,0,0] neg_lo:[0,0,1] neg_hi:[0,0,1]
	s_nop 0
	v_exp_f32_e32 v4, v4
	v_exp_f32_e32 v5, v5
	s_nop 0
	v_pk_add_f32 v[8:9], v[4:5], v[6:7]
	v_pk_fma_f32 v[6:7], v[150:151], s[4:5], v[216:217] op_sel_hi:[1,0,0] neg_lo:[0,0,1] neg_hi:[0,0,1]
	s_nop 0
	v_exp_f32_e32 v6, v6
	v_exp_f32_e32 v7, v7
	s_nop 0
	v_pk_add_f32 v[10:11], v[6:7], v[8:9]
	v_pk_fma_f32 v[8:9], v[152:153], s[4:5], v[216:217] op_sel_hi:[1,0,0] neg_lo:[0,0,1] neg_hi:[0,0,1]
	s_nop 0
	v_exp_f32_e32 v8, v8
	v_exp_f32_e32 v9, v9
	s_nop 0
	v_pk_add_f32 v[12:13], v[8:9], v[10:11]
	v_pk_fma_f32 v[10:11], v[154:155], s[4:5], v[216:217] op_sel_hi:[1,0,0] neg_lo:[0,0,1] neg_hi:[0,0,1]
	s_nop 0
	v_exp_f32_e32 v10, v10
	v_exp_f32_e32 v11, v11
	s_nop 0
	v_pk_add_f32 v[14:15], v[10:11], v[12:13]
	v_pk_fma_f32 v[12:13], v[156:157], s[4:5], v[216:217] op_sel_hi:[1,0,0] neg_lo:[0,0,1] neg_hi:[0,0,1]
	s_nop 0
	v_exp_f32_e32 v12, v12
	v_exp_f32_e32 v13, v13
	s_nop 0
	v_pk_add_f32 v[16:17], v[12:13], v[14:15]
	v_pk_fma_f32 v[14:15], v[158:159], s[4:5], v[216:217] op_sel_hi:[1,0,0] neg_lo:[0,0,1] neg_hi:[0,0,1]
	s_nop 0
	v_exp_f32_e32 v14, v14
	v_exp_f32_e32 v15, v15
	s_nop 0
	v_pk_add_f32 v[18:19], v[14:15], v[16:17]
	v_pk_fma_f32 v[16:17], v[128:129], s[4:5], v[216:217] op_sel_hi:[1,0,0] neg_lo:[0,0,1] neg_hi:[0,0,1]
	s_nop 0
	v_exp_f32_e32 v16, v16
	v_exp_f32_e32 v17, v17
	s_nop 0
	v_pk_add_f32 v[20:21], v[16:17], v[18:19]
	v_pk_fma_f32 v[18:19], v[130:131], s[4:5], v[216:217] op_sel_hi:[1,0,0] neg_lo:[0,0,1] neg_hi:[0,0,1]
	s_nop 0
	v_exp_f32_e32 v18, v18
	v_exp_f32_e32 v19, v19
	s_nop 0
	v_pk_add_f32 v[22:23], v[18:19], v[20:21]
	v_pk_fma_f32 v[20:21], v[132:133], s[4:5], v[216:217] op_sel_hi:[1,0,0] neg_lo:[0,0,1] neg_hi:[0,0,1]
	s_nop 0
	v_exp_f32_e32 v20, v20
	v_exp_f32_e32 v21, v21
	s_nop 0
	v_pk_add_f32 v[24:25], v[20:21], v[22:23]
	v_pk_fma_f32 v[22:23], v[134:135], s[4:5], v[216:217] op_sel_hi:[1,0,0] neg_lo:[0,0,1] neg_hi:[0,0,1]
	s_nop 0
	v_exp_f32_e32 v22, v22
	v_exp_f32_e32 v23, v23
	s_nop 0
	v_pk_add_f32 v[26:27], v[22:23], v[24:25]
	v_pk_fma_f32 v[24:25], v[136:137], s[4:5], v[216:217] op_sel_hi:[1,0,0] neg_lo:[0,0,1] neg_hi:[0,0,1]
	s_nop 0
	v_exp_f32_e32 v24, v24
	v_exp_f32_e32 v25, v25
	s_nop 0
	v_pk_add_f32 v[28:29], v[24:25], v[26:27]
	v_pk_fma_f32 v[26:27], v[138:139], s[4:5], v[216:217] op_sel_hi:[1,0,0] neg_lo:[0,0,1] neg_hi:[0,0,1]
	s_nop 0
	v_exp_f32_e32 v26, v26
	v_exp_f32_e32 v27, v27
	s_nop 0
	v_pk_add_f32 v[30:31], v[26:27], v[28:29]
	v_pk_fma_f32 v[28:29], v[140:141], s[4:5], v[216:217] op_sel_hi:[1,0,0] neg_lo:[0,0,1] neg_hi:[0,0,1]
	s_nop 0
	v_exp_f32_e32 v28, v28
	v_exp_f32_e32 v29, v29
	s_nop 0
	v_pk_add_f32 v[246:247], v[28:29], v[30:31]
	v_pk_fma_f32 v[30:31], v[142:143], s[4:5], v[216:217] op_sel_hi:[1,0,0] neg_lo:[0,0,1] neg_hi:[0,0,1]
	s_mov_b64 s[4:5], 0
	v_exp_f32_e32 v30, v30
	v_exp_f32_e32 v31, v31
	s_nop 0
	v_pk_add_f32 v[246:247], v[30:31], v[246:247]
	s_nop 0
	v_add_f32_e32 v245, v246, v247

.LBB0_330:
	s_nop 8
	v_mov_b32_e32 v128, v245
	v_cvt_pk_bf16_f32 v130, v4, v5
	v_cvt_pk_bf16_f32 v4, v16, v17
	v_add3_u32 v16, v242, v236, v237
	v_cvt_pk_bf16_f32 v8, v8, v9
	v_cvt_pk_bf16_f32 v9, v10, v11
	v_cvt_pk_bf16_f32 v10, v12, v13
	v_cvt_pk_bf16_f32 v11, v14, v15
	ds_read_b64_tr_b16 v[12:13], v16 offset:9216
	ds_read_b64_tr_b16 v[14:15], v16 offset:10368
	v_permlane32_swap_b32_e32 v245, v128
	v_add_f32_e32 v132, v245, v128
	v_cvt_pk_bf16_f32 v128, v0, v1
	v_cvt_pk_bf16_f32 v129, v2, v3
	v_cvt_pk_bf16_f32 v131, v6, v7
	v_cvt_pk_bf16_f32 v5, v18, v19
	v_cvt_pk_bf16_f32 v6, v20, v21
	v_cvt_pk_bf16_f32 v7, v22, v23
	v_cvt_pk_bf16_f32 v0, v24, v25
	v_cvt_pk_bf16_f32 v1, v26, v27
	v_cvt_pk_bf16_f32 v2, v28, v29
	v_cvt_pk_bf16_f32 v3, v30, v31
	ds_read_b64_tr_b16 v[18:19], v16 offset:11520
	ds_read_b64_tr_b16 v[20:21], v16 offset:12672
	ds_read_b64_tr_b16 v[22:23], v16 offset:13824
	ds_read_b64_tr_b16 v[24:25], v16 offset:14976
	ds_read_b64_tr_b16 v[26:27], v16 offset:16128
	ds_read_b64_tr_b16 v[28:29], v16 offset:17280
	v_pk_mul_f32 v[112:113], v[112:113], v[218:219] op_sel_hi:[1,0]
	v_pk_mul_f32 v[114:115], v[218:219], v[114:115] op_sel_hi:[0,1]
	v_pk_mul_f32 v[116:117], v[218:219], v[116:117] op_sel_hi:[0,1]
	v_pk_mul_f32 v[118:119], v[218:219], v[118:119] op_sel_hi:[0,1]
	v_pk_mul_f32 v[120:121], v[218:219], v[120:121] op_sel_hi:[0,1]
	v_pk_mul_f32 v[122:123], v[218:219], v[122:123] op_sel_hi:[0,1]
	v_pk_mul_f32 v[124:125], v[218:219], v[124:125] op_sel_hi:[0,1]
	v_pk_mul_f32 v[126:127], v[218:219], v[126:127] op_sel_hi:[0,1]
	s_nop 1
	s_waitcnt lgkmcnt(6)
	v_mfma_f32_32x32x16_bf16 v[112:127], v[12:15], v[128:131], v[112:127]
	ds_read_b64_tr_b16 v[12:13], v16 offset:9280
	ds_read_b64_tr_b16 v[14:15], v16 offset:10432
	v_pk_mul_f32 v[96:97], v[96:97], v[218:219] op_sel_hi:[1,0]
	s_nop 1
	s_waitcnt lgkmcnt(6)
	v_mfma_f32_32x32x16_bf16 v[112:127], v[18:21], v[8:11], v[112:127]
	ds_read_b64_tr_b16 v[18:19], v16 offset:11584
	ds_read_b64_tr_b16 v[20:21], v16 offset:12736
	v_mul_f32_e64 v98, v218, v98
	v_mul_f32_e64 v99, v218, v99
	v_mul_f32_e64 v100, v218, v100
	v_mul_f32_e64 v101, v218, v101
	v_pk_mul_f32 v[102:103], v[218:219], v[102:103] op_sel_hi:[0,1]
	v_pk_mul_f32 v[104:105], v[218:219], v[104:105] op_sel_hi:[0,1]
	v_pk_mul_f32 v[106:107], v[218:219], v[106:107] op_sel_hi:[0,1]
	v_pk_mul_f32 v[108:109], v[218:219], v[108:109] op_sel_hi:[0,1]
	s_nop 1
	s_waitcnt lgkmcnt(6)
	v_mfma_f32_32x32x16_bf16 v[112:127], v[22:25], v[4:7], v[112:127]
	ds_read_b64_tr_b16 v[22:23], v16 offset:13888
	ds_read_b64_tr_b16 v[24:25], v16 offset:15040
	v_mul_f32_e64 v110, v218, v110
	v_mul_f32_e64 v111, v218, v111
	v_fmac_f32_e32 v132, v243, v218
	s_add_i32 s10, s10, 64
	s_andn2_b64 vcc, exec, s[6:7]
	s_nop 1
	s_waitcnt lgkmcnt(6)
	v_mfma_f32_32x32x16_bf16 v[112:127], v[26:29], v[0:3], v[112:127]
	ds_read_b64_tr_b16 v[26:27], v16 offset:16192
	ds_read_b64_tr_b16 v[28:29], v16 offset:17344
	s_waitcnt lgkmcnt(6)
	v_mfma_f32_32x32x16_bf16 v[96:111], v[12:15], v[128:131], v[96:111]
	s_waitcnt lgkmcnt(4)
	v_mfma_f32_32x32x16_bf16 v[96:111], v[18:21], v[8:11], v[96:111]
	s_waitcnt lgkmcnt(2)
	v_mfma_f32_32x32x16_bf16 v[96:111], v[22:25], v[4:7], v[96:111]
	s_waitcnt lgkmcnt(0)
	v_mfma_f32_32x32x16_bf16 v[96:111], v[26:29], v[0:3], v[96:111]
	v_cndmask_b32_e64 v0, 0, 1, s[8:9]
	v_xor_b32_e32 v241, v241, v0
	s_cbranch_vccz .LBB0_332
	v_mov_b32_e32 v243, v132
	v_mov_b32_e32 v244, v216
	s_branch .LBB0_326
